# lazy softmax rescale (O rescaled only when the row max grows by more than 4 log2 units) in all five attention loops, half-used v_pk_add_f32 replaced by v_add_f32
# speedup vs baseline: 1.0412x; 1.0251x over previous
; #define LAS __attribute__((address_space(3)))
; #define MFMA32(a, b, c) __builtin_amdgcn_mfma_f32_32x32x16_bf16((a), (b), (c), 0, 0, 0)
; template <int DQK, int VAR> __device__ __forceinline__ void att_tile(LAS unsigned char* lds, int kt, int mylast, int grp, bool& pend, int vs_prev, int vs_cur, int lane_off, int r, int h, ...
;     ...
;     if (kt <= mylast) {
;         f32x16 S0, S1;
; #pragma unroll
;         for (int i = 0; i < 16; ++i) { S0[i] = 0.f; S1[i] = 0.f; }
;         const LAS unsigned char* kb = lds + (kt & 1) * ATT_KBYTES + r * KP + h * 16;
;         bf16x8 ka[3][2];
;         ka[0][0] = *(const LAS bf16x8*)(kb); ka[0][1] = *(const LAS bf16x8*)(kb + 32 * KP);
;         ka[1][0] = *(const LAS bf16x8*)(kb + 32); ka[1][1] = *(const LAS bf16x8*)(kb + 32 * KP + 32);
; #pragma unroll
;         for (int s = 0; s < NS; ++s) {
;             if (s + 2 < NS) { ka[(s + 2) % 3][0] = *(const LAS bf16x8*)(kb + (s + 2) * 32); ka[(s + 2) % 3][1] = *(const LAS bf16x8*)(kb + 32 * KP + (s + 2) * 32); }
;             if (VAR == 4) { S0[s & 15] += __builtin_bit_cast(f32x4, ka[s % 3][0])[0] * __builtin_bit_cast(f32x4, qf[s])[1]; S1[s & 15] += __builtin_bit_cast(f32x4, ka[s % 3][1])[2]; }
;             else { S0 = MFMA32(ka[s % 3][0], qf[s], S0); S1 = MFMA32(ka[s % 3][1], qf[s], S1); }
;             __builtin_amdgcn_sched_barrier(0);
;         }
;         if (VAR != 5) {
;         float mx = S0[0];
; #pragma unroll
;         for (int i = 1; i < 16; ++i) mx = fmaxf(mx, S0[i]);
; #pragma unroll
;         for (int i = 0; i < 16; ++i) mx = fmaxf(mx, S1[i]);
;         mx = fmaxf(mx, __shfl_xor(mx, 32));
;         const float mn = fmaxf(mrun, mx), alpha = __builtin_amdgcn_exp2f(mrun - mn);
;         const bool grew = __builtin_amdgcn_ballot_w64(mn > mrun) != 0ull;
;         mrun = mn;
;         float ps = 0.f;
; #pragma unroll
;         for (int i = 0; i < 16; ++i) { S0[i] = (VAR == 2) ? (S0[i] - mn) : __builtin_amdgcn_exp2f(S0[i] - mn); ps += S0[i]; }
; #pragma unroll
;         for (int i = 0; i < 16; ++i) { S1[i] = (VAR == 2) ? (S1[i] - mn) : __builtin_amdgcn_exp2f(S1[i] - mn); ps += S1[i]; }
;         lrun = lrun * alpha + ps;
;         if (grew) {
; #pragma unroll
;             for (int db = 0; db < 4; ++db) O[db] = O[db] * alpha;
;         }
.LBB0_769:
	s_cmp_gt_i32 s27, s69
	s_cbranch_scc1 .LBB0_773
	s_bitcmp1_b32 s27, 0
	s_cselect_b32 s26, 0x6400, 0
	v_add_u32_e32 v0, s26, v191
	ds_read_b128 v[66:69], v0
	ds_read_b128 v[196:199], v0 offset:32
	s_waitcnt lgkmcnt(1)
	v_mfma_f32_32x32x16_bf16 v[82:97], v[66:69], v[98:101], 0
	ds_read_b128 v[66:69], v0 offset:12800
	ds_read_b128 v[212:215], v0 offset:64
	ds_read_b128 v[216:219], v0 offset:12832
	ds_read_b128 v[220:223], v0 offset:12864
	s_waitcnt lgkmcnt(3)
	v_mfma_f32_32x32x16_bf16 v[66:81], v[66:69], v[98:101], 0
	v_mfma_f32_32x32x16_bf16 v[82:97], v[196:199], v[102:105], v[82:97]
	ds_read_b128 v[196:199], v0 offset:96
	ds_read_b128 v[230:233], v0 offset:12896
	s_waitcnt lgkmcnt(3)
	v_mfma_f32_32x32x16_bf16 v[66:81], v[216:219], v[102:105], v[66:81]
	v_mfma_f32_32x32x16_bf16 v[82:97], v[212:215], v[106:109], v[82:97]
	ds_read_b128 v[212:215], v0 offset:128
	ds_read_b128 v[216:219], v0 offset:12928
	s_waitcnt lgkmcnt(4)
	v_mfma_f32_32x32x16_bf16 v[66:81], v[220:223], v[106:109], v[66:81]
	s_waitcnt lgkmcnt(3)
	v_mfma_f32_32x32x16_bf16 v[82:97], v[196:199], v[110:113], v[82:97]
	ds_read_b128 v[196:199], v0 offset:160
	ds_read_b128 v[220:223], v0 offset:12960
	s_waitcnt lgkmcnt(4)
	v_mfma_f32_32x32x16_bf16 v[66:81], v[230:233], v[110:113], v[66:81]
	s_waitcnt lgkmcnt(3)
	v_mfma_f32_32x32x16_bf16 v[82:97], v[212:215], v[114:117], v[82:97]
	ds_read_b128 v[212:215], v0 offset:192
	ds_read_b128 v[230:233], v0 offset:12992
	s_waitcnt lgkmcnt(4)
	v_mfma_f32_32x32x16_bf16 v[66:81], v[216:219], v[114:117], v[66:81]
	s_waitcnt lgkmcnt(3)
	v_mfma_f32_32x32x16_bf16 v[82:97], v[196:199], v[118:121], v[82:97]
	ds_read_b128 v[196:199], v0 offset:224
	ds_read_b128 v[216:219], v0 offset:13024
	s_waitcnt lgkmcnt(4)
	v_mfma_f32_32x32x16_bf16 v[66:81], v[220:223], v[118:121], v[66:81]
	s_waitcnt lgkmcnt(3)
	v_mfma_f32_32x32x16_bf16 v[82:97], v[212:215], v[122:125], v[82:97]
	ds_read_b128 v[212:215], v0 offset:256
	ds_read_b128 v[220:223], v0 offset:13056
	s_waitcnt lgkmcnt(4)
	v_mfma_f32_32x32x16_bf16 v[66:81], v[230:233], v[122:125], v[66:81]
	s_waitcnt lgkmcnt(3)
	v_mfma_f32_32x32x16_bf16 v[82:97], v[196:199], v[126:129], v[82:97]
	ds_read_b128 v[196:199], v0 offset:288
	ds_read_b128 v[230:233], v0 offset:13088
	s_waitcnt lgkmcnt(4)
	v_mfma_f32_32x32x16_bf16 v[66:81], v[216:219], v[126:129], v[66:81]
	s_waitcnt lgkmcnt(3)
	v_mfma_f32_32x32x16_bf16 v[82:97], v[212:215], v[130:133], v[82:97]
	ds_read_b128 v[212:215], v0 offset:320
	ds_read_b128 v[216:219], v0 offset:13120
	s_waitcnt lgkmcnt(4)
	v_mfma_f32_32x32x16_bf16 v[66:81], v[220:223], v[130:133], v[66:81]
	s_waitcnt lgkmcnt(3)
	v_mfma_f32_32x32x16_bf16 v[82:97], v[196:199], v[134:137], v[82:97]
	ds_read_b128 v[196:199], v0 offset:352
	ds_read_b128 v[220:223], v0 offset:13152
	s_waitcnt lgkmcnt(4)
	v_mfma_f32_32x32x16_bf16 v[66:81], v[230:233], v[134:137], v[66:81]
	s_waitcnt lgkmcnt(3)
	v_mfma_f32_32x32x16_bf16 v[82:97], v[212:215], v[138:141], v[82:97]
	s_waitcnt lgkmcnt(2)
	v_mfma_f32_32x32x16_bf16 v[66:81], v[216:219], v[138:141], v[66:81]
	s_waitcnt lgkmcnt(1)
	v_mfma_f32_32x32x16_bf16 v[82:97], v[196:199], v[142:145], v[82:97]
	s_nop 11
	v_max_f32_e32 v0, v83, v83
	v_max_f32_e32 v193, v82, v82
	v_max_f32_e32 v0, v193, v0
	s_waitcnt lgkmcnt(0)
	v_mfma_f32_32x32x16_bf16 v[66:81], v[220:223], v[142:145], v[66:81]
	v_max3_f32 v0, v0, v84, v85
	v_max3_f32 v0, v0, v86, v87
	v_max3_f32 v0, v0, v88, v89
	v_max3_f32 v0, v0, v90, v91
	v_max3_f32 v0, v0, v92, v93
	v_max3_f32 v0, v0, v94, v95
	v_max3_f32 v0, v0, v96, v97
	s_nop 4
	v_max3_f32 v0, v0, v66, v67
	v_max3_f32 v0, v0, v68, v69
	v_max3_f32 v0, v0, v70, v71
	v_max3_f32 v0, v0, v72, v73
	v_max3_f32 v0, v0, v74, v75
	v_max3_f32 v0, v0, v76, v77
	v_max3_f32 v0, v0, v78, v79
	v_max3_f32 v0, v0, v80, v81
	ds_bpermute_b32 v193, v225, v0
	s_waitcnt lgkmcnt(0)
	v_max3_f32 v193, v194, v0, v193
	v_sub_f32_e32 v0, v193, v194
	v_cmp_lt_f32_e32 vcc, 4.0, v0
	v_cndmask_b32_e32 v193, v194, v193, vcc
	v_sub_f32_e32 v0, v194, v193
	v_exp_f32_e32 v0, v0
	v_cmp_gt_f32_e32 vcc, v193, v194
	s_cbranch_vccz .LBB0_772
	v_pk_mul_f32 v[16:17], v[16:17], v[0:1] op_sel_hi:[1,0]
	v_pk_mul_f32 v[14:15], v[14:15], v[0:1] op_sel_hi:[1,0]
	v_pk_mul_f32 v[12:13], v[12:13], v[0:1] op_sel_hi:[1,0]
	v_pk_mul_f32 v[10:11], v[10:11], v[0:1] op_sel_hi:[1,0]
	v_pk_mul_f32 v[8:9], v[8:9], v[0:1] op_sel_hi:[1,0]
	v_pk_mul_f32 v[6:7], v[6:7], v[0:1] op_sel_hi:[1,0]
	v_pk_mul_f32 v[4:5], v[4:5], v[0:1] op_sel_hi:[1,0]
	v_pk_mul_f32 v[2:3], v[2:3], v[0:1] op_sel_hi:[1,0]
	v_pk_mul_f32 v[32:33], v[32:33], v[0:1] op_sel_hi:[1,0]
	v_pk_mul_f32 v[30:31], v[30:31], v[0:1] op_sel_hi:[1,0]
	v_pk_mul_f32 v[28:29], v[28:29], v[0:1] op_sel_hi:[1,0]
	v_pk_mul_f32 v[26:27], v[26:27], v[0:1] op_sel_hi:[1,0]
	v_pk_mul_f32 v[24:25], v[24:25], v[0:1] op_sel_hi:[1,0]
	v_pk_mul_f32 v[22:23], v[22:23], v[0:1] op_sel_hi:[1,0]
	v_pk_mul_f32 v[20:21], v[20:21], v[0:1] op_sel_hi:[1,0]
	v_pk_mul_f32 v[18:19], v[18:19], v[0:1] op_sel_hi:[1,0]
	v_pk_mul_f32 v[48:49], v[48:49], v[0:1] op_sel_hi:[1,0]
	v_pk_mul_f32 v[46:47], v[46:47], v[0:1] op_sel_hi:[1,0]
	v_pk_mul_f32 v[44:45], v[44:45], v[0:1] op_sel_hi:[1,0]
	v_pk_mul_f32 v[42:43], v[42:43], v[0:1] op_sel_hi:[1,0]
	v_pk_mul_f32 v[40:41], v[40:41], v[0:1] op_sel_hi:[1,0]
	v_pk_mul_f32 v[38:39], v[38:39], v[0:1] op_sel_hi:[1,0]
	v_pk_mul_f32 v[36:37], v[36:37], v[0:1] op_sel_hi:[1,0]
	v_pk_mul_f32 v[34:35], v[34:35], v[0:1] op_sel_hi:[1,0]
	v_pk_mul_f32 v[64:65], v[64:65], v[0:1] op_sel_hi:[1,0]
	v_pk_mul_f32 v[62:63], v[62:63], v[0:1] op_sel_hi:[1,0]
	v_pk_mul_f32 v[60:61], v[60:61], v[0:1] op_sel_hi:[1,0]
	v_pk_mul_f32 v[58:59], v[58:59], v[0:1] op_sel_hi:[1,0]
	v_pk_mul_f32 v[56:57], v[56:57], v[0:1] op_sel_hi:[1,0]
	v_pk_mul_f32 v[54:55], v[54:55], v[0:1] op_sel_hi:[1,0]
	v_pk_mul_f32 v[52:53], v[52:53], v[0:1] op_sel_hi:[1,0]
	v_pk_mul_f32 v[50:51], v[50:51], v[0:1] op_sel_hi:[1,0]

; #define LAS __attribute__((address_space(3)))
; #define MFMA32(a, b, c) __builtin_amdgcn_mfma_f32_32x32x16_bf16((a), (b), (c), 0, 0, 0)
; template <int DQK, int VAR> __device__ __forceinline__ void att_tile_fused(LAS unsigned char* lds, int kt, int mylast, bool& pend, int vs_prev, int vs_cur, int lane_off, int r, int h, ...
;     ...
;     f32x16 S0, S1;
; #pragma unroll
;     for (int i = 0; i < 16; ++i) { S0[i] = 0.f; S1[i] = 0.f; }
;     const LAS unsigned char* kb = lds + (kt & 1) * ATT_KBYTES + r * KP + h * 16;
;     bf16x8 ka[2][2];
;     ka[0][0] = *(const LAS bf16x8*)(kb); ka[0][1] = *(const LAS bf16x8*)(kb + 32 * KP);
; #pragma unroll
;     for (int s = 0; s < NS; ++s) {
;         if (s + 1 < NS) { ka[(s + 1) & 1][0] = *(const LAS bf16x8*)(kb + (s + 1) * 32); ka[(s + 1) & 1][1] = *(const LAS bf16x8*)(kb + 32 * KP + (s + 1) * 32); }
;         S0 = MFMA32(ka[s & 1][0], qf[s], S0); S1 = MFMA32(ka[s & 1][1], qf[s], S1);
;         __builtin_amdgcn_sched_barrier(0);
;     }
;     const LAS unsigned char* vb = lds + ATT_VOFF + (pend ? vs_prev : vs_cur) * ATT_VBYTES + lane_off;
;     bf16x8 va[2][4];
; #pragma unroll
;     for (int js = 0; js < 4; ++js) va[0][js] = *(const LAS bf16x8*)(vb + js * 32);
;     float mx = S0[0];
; #pragma unroll
;     for (int i = 1; i < 16; ++i) mx = fmaxf(mx, S0[i]);
; #pragma unroll
;     for (int i = 0; i < 16; ++i) mx = fmaxf(mx, S1[i]);
;     mx = fmaxf(mx, __shfl_xor(mx, 32));
;     const float mn = fmaxf(mrun, mx), alpha = __builtin_amdgcn_exp2f(mrun - mn);
;     const bool grew = __builtin_amdgcn_ballot_w64(mn > mrun) != 0ull;
;     mrun = mn;
;     float ps = 0.f;
;     u32x4 w0, w1, w2, w3;
;     __builtin_amdgcn_sched_barrier(0);
; #pragma unroll
;     for (int db = 0; db < 4; ++db) {
;         if (db < 3) {
; #pragma unroll
;             for (int js = 0; js < 4; ++js) va[(db + 1) & 1][js] = *(const LAS bf16x8*)(vb + (db + 1) * 32 * VPB + js * 32);
;         }
; #pragma unroll
;         for (int js = 0; js < 4; ++js) {
;             const int c = db * 4 + js;
;             O[db] = MFMA32(va[db & 1][js], pf[js], O[db]);
;             S0[c] = __builtin_amdgcn_exp2f(S0[c] - mn); S1[c] = __builtin_amdgcn_exp2f(S1[c] - mn); ps += S0[c] + S1[c];
.LBB0_799:
	s_andn2_b64 vcc, exec, s[36:37]
	s_mov_b64 s[36:37], 0
	s_cbranch_vccnz .LBB0_801
	v_add_u32_e32 v0, v230, v212
	ds_read_b128 v[2:5], v0
	ds_read_b128 v[6:9], v0 offset:32
	s_waitcnt lgkmcnt(1)
	v_mfma_f32_32x32x16_bf16 v[80:95], v[2:5], v[144:147], 0
	ds_read_b128 v[2:5], v0 offset:4608
	ds_read_b128 v[10:13], v0 offset:4640
	s_waitcnt lgkmcnt(1)
	v_mfma_f32_32x32x16_bf16 v[96:111], v[2:5], v[144:147], 0
	v_mfma_f32_32x32x16_bf16 v[80:95], v[6:9], v[156:159], v[80:95]
	ds_read_b128 v[2:5], v0 offset:64
	ds_read_b128 v[6:9], v0 offset:4672
	s_waitcnt lgkmcnt(2)
	v_mfma_f32_32x32x16_bf16 v[96:111], v[10:13], v[156:159], v[96:111]
	s_waitcnt lgkmcnt(1)
	v_mfma_f32_32x32x16_bf16 v[80:95], v[2:5], v[160:163], v[80:95]
	ds_read_b128 v[2:5], v0 offset:96
	ds_read_b128 v[10:13], v0 offset:4704
	s_waitcnt lgkmcnt(2)
	v_mfma_f32_32x32x16_bf16 v[96:111], v[6:9], v[160:163], v[96:111]
	s_waitcnt lgkmcnt(1)
	v_mfma_f32_32x32x16_bf16 v[80:95], v[2:5], v[168:171], v[80:95]
	s_and_b64 s[34:35], s[34:35], exec
	s_cselect_b32 s14, s27, s74
	s_mulk_i32 s14, 0x4800
	v_add_u32_e32 v132, s14, v233
	s_waitcnt lgkmcnt(0)
	v_mfma_f32_32x32x16_bf16 v[96:111], v[10:13], v[168:171], v[96:111]
	s_nop 5
	v_max_f32_e32 v0, v81, v81
	v_max_f32_e32 v2, v80, v80
	v_max_f32_e32 v0, v2, v0
	v_max3_f32 v0, v0, v82, v83
	v_max3_f32 v0, v0, v84, v85
	v_max3_f32 v0, v0, v86, v87
	v_max3_f32 v0, v0, v88, v89
	v_max3_f32 v0, v0, v90, v91
	v_max3_f32 v0, v0, v92, v93
	v_max3_f32 v0, v0, v94, v95
	v_max3_f32 v0, v0, v96, v97
	v_max3_f32 v0, v0, v98, v99
	v_max3_f32 v0, v0, v100, v101
	v_max3_f32 v0, v0, v102, v103
	v_max3_f32 v0, v0, v104, v105
	v_max3_f32 v0, v0, v106, v107
	v_max3_f32 v0, v0, v108, v109
	v_max3_f32 v0, v0, v110, v111
	ds_bpermute_b32 v14, v225, v0
	ds_read_b128 v[2:5], v132 offset:51200
	ds_read_b128 v[6:9], v132 offset:51232
	ds_read_b128 v[10:13], v132 offset:51264
	ds_read_b128 v[112:115], v132 offset:51296
	s_waitcnt lgkmcnt(4)
	v_max3_f32 v236, v235, v0, v14
	v_sub_f32_e32 v133, v236, v235
	v_cmp_lt_f32_e32 vcc, 4.0, v133
	v_cndmask_b32_e32 v236, v235, v236, vcc
	v_cmp_gt_f32_e32 vcc, v236, v235
	s_cmp_lg_u64 vcc, 0
	v_sub_f32_e32 v133, v235, v236
	s_cselect_b64 s[36:37], -1, 0
	ds_read_b128 v[116:119], v132 offset:55808
	ds_read_b128 v[120:123], v132 offset:55840
	ds_read_b128 v[124:127], v132 offset:55872
	ds_read_b128 v[128:131], v132 offset:55904
	v_sub_f32_e32 v0, v80, v236
	v_exp_f32_e32 v14, v0
	v_sub_f32_e32 v0, v96, v236
	v_exp_f32_e32 v15, v0
	s_waitcnt lgkmcnt(7)
	v_mfma_f32_32x32x16_bf16 v[32:47], v[2:5], v[164:167], v[32:47]
	v_add_f32_e32 v3, v15, v14
	v_sub_f32_e32 v0, v81, v236
	v_sub_f32_e32 v2, v97, v236
	v_exp_f32_e32 v0, v0
	v_exp_f32_e32 v2, v2
	s_waitcnt lgkmcnt(6)
	v_mfma_f32_32x32x16_bf16 v[32:47], v[6:9], v[148:151], v[32:47]
	v_add_f32_e64 v4, v2, v0
	v_add_f32_e64 v5, v3, v1
	v_add_f32_e32 v5, v4, v5
	v_cvt_pk_bf16_f32 v237, v15, v2
	v_cvt_pk_bf16_f32 v0, v14, v0
	v_sub_f32_e32 v2, v82, v236
	v_exp_f32_e32 v8, v2
	v_sub_f32_e32 v2, v98, v236
	v_exp_f32_e32 v9, v2
	s_waitcnt lgkmcnt(5)
	v_mfma_f32_32x32x16_bf16 v[32:47], v[10:13], v[172:175], v[32:47]
	v_add_f32_e32 v3, v9, v8
	v_sub_f32_e32 v2, v83, v236
	v_exp_f32_e32 v4, v2
	v_sub_f32_e32 v2, v99, v236
	v_exp_f32_e32 v2, v2
	s_waitcnt lgkmcnt(4)
	v_mfma_f32_32x32x16_bf16 v[32:47], v[112:115], v[152:155], v[32:47]
	v_cvt_pk_bf16_f32 v238, v8, v4
	v_add_f32_e64 v6, v2, v4
	v_add_f32_e64 v7, v3, v5
	v_add_f32_e64 v14, v6, v6
	v_add_f32_e64 v15, v6, v7
	v_cvt_pk_bf16_f32 v239, v9, v2
	ds_read_b128 v[2:5], v132 offset:60416
	ds_read_b128 v[6:9], v132 offset:60448
	ds_read_b128 v[10:13], v132 offset:60480
	ds_read_b128 v[80:83], v132 offset:60512
	v_sub_f32_e32 v14, v84, v236
	v_exp_f32_e32 v98, v14
	v_sub_f32_e32 v14, v100, v236
	v_exp_f32_e32 v99, v14
	s_waitcnt lgkmcnt(7)
	v_mfma_f32_32x32x16_bf16 v[64:79], v[116:119], v[164:167], v[64:79]
	v_add_f32_e32 v97, v99, v98
	v_sub_f32_e32 v14, v85, v236
	v_sub_f32_e32 v84, v101, v236
	v_exp_f32_e32 v14, v14
	v_exp_f32_e32 v96, v84
	s_waitcnt lgkmcnt(6)
	v_mfma_f32_32x32x16_bf16 v[64:79], v[120:123], v[148:151], v[64:79]
	v_cvt_pk_bf16_f32 v240, v98, v14
	v_add_f32_e64 v84, v96, v14
	v_add_f32_e64 v85, v97, v15
	v_cvt_pk_bf16_f32 v241, v99, v96
	v_add_f32_e32 v85, v84, v85
	v_sub_f32_e32 v14, v86, v236
	v_exp_f32_e32 v96, v14
	v_sub_f32_e32 v14, v102, v236
	v_exp_f32_e32 v97, v14
	s_waitcnt lgkmcnt(5)
; #define LAS __attribute__((address_space(3)))
; __device__ __forceinline__ unsigned pk2(float lo, float hi) { f32x2_t v = {lo, hi}; bf16x2_t b = __builtin_convertvector(v, bf16x2_t); return __builtin_bit_cast(unsigned, b); }
; #define MFMA32(a, b, c) __builtin_amdgcn_mfma_f32_32x32x16_bf16((a), (b), (c), 0, 0, 0)
; template <int DQK, int VAR> __device__ __forceinline__ void att_tile_fused(LAS unsigned char* lds, int kt, int mylast, bool& pend, int vs_prev, int vs_cur, int lane_off, int r, int h, ...
;     ...
; #pragma unroll
;     for (int db = 0; db < 4; ++db) {
;         if (db < 3) {
; #pragma unroll
;             for (int js = 0; js < 4; ++js) va[(db + 1) & 1][js] = *(const LAS bf16x8*)(vb + (db + 1) * 32 * VPB + js * 32);
;         }
; #pragma unroll
;         for (int js = 0; js < 4; ++js) {
;             const int c = db * 4 + js;
;             O[db] = MFMA32(va[db & 1][js], pf[js], O[db]);
;             S0[c] = __builtin_amdgcn_exp2f(S0[c] - mn); S1[c] = __builtin_amdgcn_exp2f(S1[c] - mn); ps += S0[c] + S1[c];
;             if (c & 1) {
;                 const unsigned a = pk2(S0[c - 1], S0[c]), b = pk2(S1[c - 1], S1[c]);
;                 const int q = c >> 1;
;                 if (q == 0) { w0.x = a; w2.x = b; } else if (q == 1) { w0.y = a; w2.y = b; } else if (q == 2) { w0.z = a; w2.z = b; } else if (q == 3) { w0.w = a; w2.w = b; }
;                 else if (q == 4) { w1.x = a; w3.x = b; } else if (q == 5) { w1.y = a; w3.y = b; } else if (q == 6) { w1.z = a; w3.z = b; } else { w1.w = a; w3.w = b; }
;             }
;             __builtin_amdgcn_sched_barrier(0);
;         }
;     }
;     lrun = lrun * alpha + ps;
;     alpha_p = alpha; grew_p = grew;
;     pf[0] = __builtin_bit_cast(bf16x8, w0); pf[1] = __builtin_bit_cast(bf16x8, w1); pf[2] = __builtin_bit_cast(bf16x8, w2); pf[3] = __builtin_bit_cast(bf16x8, w3);
;     pend = true;
	v_mfma_f32_32x32x16_bf16 v[64:79], v[124:127], v[172:175], v[64:79]
	v_add_f32_e32 v15, v97, v96
	v_sub_f32_e32 v14, v87, v236
	v_exp_f32_e32 v84, v14
	v_sub_f32_e32 v14, v103, v236
	v_exp_f32_e32 v14, v14
	s_waitcnt lgkmcnt(4)
	v_mfma_f32_32x32x16_bf16 v[64:79], v[128:131], v[152:155], v[64:79]
	v_add_f32_e64 v86, v14, v84
	v_add_f32_e64 v87, v15, v85
	v_add_f32_e64 v116, v86, v86
	v_add_f32_e64 v117, v86, v87
	v_cvt_pk_bf16_f32 v15, v96, v84
	v_cvt_pk_bf16_f32 v14, v97, v14
	ds_read_b128 v[84:87], v132 offset:65024
	ds_read_b128 v[96:99], v132 offset:65056
	ds_read_b128 v[100:103], v132 offset:65088
	ds_read_b128 v[112:115], v132 offset:65120
	v_sub_f32_e32 v88, v88, v236
	v_sub_f32_e32 v104, v104, v236
	v_exp_f32_e32 v88, v88
	v_exp_f32_e32 v104, v104
	s_waitcnt lgkmcnt(7)
	v_mfma_f32_32x32x16_bf16 v[48:63], v[2:5], v[164:167], v[48:63]
	v_add_f32_e32 v3, v104, v88
	v_sub_f32_e32 v2, v89, v236
	v_exp_f32_e32 v116, v2
	v_sub_f32_e32 v2, v105, v236
	v_exp_f32_e32 v2, v2
	s_waitcnt lgkmcnt(6)
	v_mfma_f32_32x32x16_bf16 v[48:63], v[6:9], v[148:151], v[48:63]
	v_cvt_pk_bf16_f32 v8, v88, v116
	v_add_f32_e64 v4, v2, v116
	v_add_f32_e64 v5, v3, v117
	v_add_f32_e32 v5, v4, v5
	v_cvt_pk_bf16_f32 v9, v104, v2
	v_sub_f32_e32 v2, v90, v236
	v_exp_f32_e32 v88, v2
	v_sub_f32_e32 v2, v106, v236
	v_exp_f32_e32 v89, v2
	s_waitcnt lgkmcnt(5)
	v_mfma_f32_32x32x16_bf16 v[48:63], v[10:13], v[172:175], v[48:63]
	v_add_f32_e32 v3, v89, v88
	v_sub_f32_e32 v2, v91, v236
	v_exp_f32_e32 v4, v2
	v_sub_f32_e32 v2, v107, v236
	v_exp_f32_e32 v2, v2
	s_waitcnt lgkmcnt(4)
	v_mfma_f32_32x32x16_bf16 v[48:63], v[80:83], v[152:155], v[48:63]
	v_cvt_pk_bf16_f32 v10, v88, v4
	v_add_f32_e64 v6, v2, v4
	v_add_f32_e64 v7, v3, v5
	v_add_f32_e32 v7, v6, v7
	v_cvt_pk_bf16_f32 v11, v89, v2
	v_sub_f32_e32 v2, v92, v236
	v_exp_f32_e32 v12, v2
	v_sub_f32_e32 v2, v108, v236
	v_exp_f32_e32 v13, v2
	s_waitcnt lgkmcnt(3)
	v_mfma_f32_32x32x16_bf16 v[16:31], v[84:87], v[164:167], v[16:31]
	v_add_f32_e32 v3, v13, v12
	v_sub_f32_e32 v2, v93, v236
	v_exp_f32_e32 v6, v2
	v_sub_f32_e32 v2, v109, v236
	v_exp_f32_e32 v2, v2
	s_waitcnt lgkmcnt(2)
	v_mfma_f32_32x32x16_bf16 v[16:31], v[96:99], v[148:151], v[16:31]
	v_cvt_pk_bf16_f32 v150, v12, v6
	v_add_f32_e64 v4, v2, v6
	v_add_f32_e64 v5, v3, v7
	v_add_f32_e32 v5, v4, v5
	v_cvt_pk_bf16_f32 v12, v13, v2
	v_sub_f32_e32 v2, v94, v236
	v_exp_f32_e32 v13, v2
	v_sub_f32_e32 v2, v110, v236
	v_exp_f32_e32 v80, v2
	s_waitcnt lgkmcnt(1)
	v_mfma_f32_32x32x16_bf16 v[16:31], v[100:103], v[172:175], v[16:31]
	v_add_f32_e32 v3, v80, v13
	v_sub_f32_e32 v2, v95, v236
	v_exp_f32_e32 v4, v2
	v_sub_f32_e32 v2, v111, v236
	v_exp_f32_e32 v2, v2
	s_waitcnt lgkmcnt(0)
	v_mfma_f32_32x32x16_bf16 v[16:31], v[112:115], v[152:155], v[16:31]
	v_cvt_pk_bf16_f32 v151, v13, v4
	v_add_f32_e64 v6, v2, v4
	v_add_f32_e64 v7, v3, v5
	v_cvt_pk_bf16_f32 v155, v80, v2
	v_add_f32_e32 v3, v6, v7
	v_exp_f32_e32 v224, v133
	s_nop 5
	v_mov_b64_e32 v[142:143], v[30:31]
	v_mov_b64_e32 v[126:127], v[62:63]
	v_mov_b64_e32 v[110:111], v[78:79]
	v_fmac_f32_e32 v3, v211, v224
	v_mov_b64_e32 v[94:95], v[46:47]
	v_mov_b64_e32 v[140:141], v[28:29]
	v_mov_b64_e32 v[138:139], v[26:27]
	v_mov_b64_e32 v[136:137], v[24:25]
	v_mov_b64_e32 v[134:135], v[22:23]
	v_mov_b64_e32 v[132:133], v[20:21]
	v_mov_b64_e32 v[130:131], v[18:19]
	v_mov_b64_e32 v[128:129], v[16:17]
	v_mov_b64_e32 v[124:125], v[60:61]
	v_mov_b64_e32 v[122:123], v[58:59]
	v_mov_b64_e32 v[120:121], v[56:57]
	v_mov_b64_e32 v[118:119], v[54:55]
	v_mov_b64_e32 v[116:117], v[52:53]
	v_mov_b64_e32 v[114:115], v[50:51]
	v_mov_b64_e32 v[112:113], v[48:49]
	v_mov_b64_e32 v[108:109], v[76:77]
	v_mov_b64_e32 v[106:107], v[74:75]
	v_mov_b64_e32 v[104:105], v[72:73]
	v_mov_b64_e32 v[102:103], v[70:71]
	v_mov_b64_e32 v[100:101], v[68:69]
	v_mov_b64_e32 v[98:99], v[66:67]
	v_mov_b64_e32 v[96:97], v[64:65]
	v_mov_b64_e32 v[92:93], v[44:45]
	v_mov_b64_e32 v[90:91], v[42:43]
	v_mov_b64_e32 v[88:89], v[40:41]
	v_mov_b64_e32 v[86:87], v[38:39]
	v_mov_b64_e32 v[84:85], v[36:37]
	v_mov_b64_e32 v[82:83], v[34:35]
	v_mov_b64_e32 v[80:81], v[32:33]
	v_mov_b32_e32 v235, v236
	v_mov_b32_e32 v211, v3
	v_mov_b32_e32 v164, v0
	v_mov_b32_e32 v165, v238
	v_mov_b32_e32 v166, v240
	v_mov_b32_e32 v167, v15
	v_mov_b32_e32 v148, v8
	v_mov_b32_e32 v149, v10
	v_mov_b32_e32 v172, v237
	v_mov_b32_e32 v173, v239
	v_mov_b32_e32 v174, v241
	v_mov_b32_e32 v175, v14
	v_mov_b32_e32 v152, v9
	v_mov_b32_e32 v153, v11
	v_mov_b32_e32 v154, v12

; #define LAS __attribute__((address_space(3)))
; #define MFMA32(a, b, c) __builtin_amdgcn_mfma_f32_32x32x16_bf16((a), (b), (c), 0, 0, 0)
; template <int DQK, int VAR> __device__ __forceinline__ void att_tile_fused(LAS unsigned char* lds, int kt, int mylast, bool& pend, int vs_prev, int vs_cur, int lane_off, int r, int h, ...
;     ...
;     f32x16 S0, S1;
; #pragma unroll
;     for (int i = 0; i < 16; ++i) { S0[i] = 0.f; S1[i] = 0.f; }
;     const LAS unsigned char* kb = lds + (kt & 1) * ATT_KBYTES + r * KP + h * 16;
;     bf16x8 ka[2][2];
;     ka[0][0] = *(const LAS bf16x8*)(kb); ka[0][1] = *(const LAS bf16x8*)(kb + 32 * KP);
; #pragma unroll
;     for (int s = 0; s < NS; ++s) {
;         if (s + 1 < NS) { ka[(s + 1) & 1][0] = *(const LAS bf16x8*)(kb + (s + 1) * 32); ka[(s + 1) & 1][1] = *(const LAS bf16x8*)(kb + 32 * KP + (s + 1) * 32); }
;         S0 = MFMA32(ka[s & 1][0], qf[s], S0); S1 = MFMA32(ka[s & 1][1], qf[s], S1);
;         __builtin_amdgcn_sched_barrier(0);
;     }
;     const LAS unsigned char* vb = lds + ATT_VOFF + (pend ? vs_prev : vs_cur) * ATT_VBYTES + lane_off;
;     bf16x8 va[2][4];
; #pragma unroll
;     for (int js = 0; js < 4; ++js) va[0][js] = *(const LAS bf16x8*)(vb + js * 32);
;     float mx = S0[0];
; #pragma unroll
;     for (int i = 1; i < 16; ++i) mx = fmaxf(mx, S0[i]);
; #pragma unroll
;     for (int i = 0; i < 16; ++i) mx = fmaxf(mx, S1[i]);
;     mx = fmaxf(mx, __shfl_xor(mx, 32));
;     const float mn = fmaxf(mrun, mx), alpha = __builtin_amdgcn_exp2f(mrun - mn);
;     const bool grew = __builtin_amdgcn_ballot_w64(mn > mrun) != 0ull;
;     mrun = mn;
;     float ps = 0.f;
;     u32x4 w0, w1, w2, w3;
;     __builtin_amdgcn_sched_barrier(0);
; #pragma unroll
;     for (int db = 0; db < 4; ++db) {
;         if (db < 3) {
; #pragma unroll
;             for (int js = 0; js < 4; ++js) va[(db + 1) & 1][js] = *(const LAS bf16x8*)(vb + (db + 1) * 32 * VPB + js * 32);
;         }
; #pragma unroll
;         for (int js = 0; js < 4; ++js) {
;             const int c = db * 4 + js;
;             O[db] = MFMA32(va[db & 1][js], pf[js], O[db]);
;             S0[c] = __builtin_amdgcn_exp2f(S0[c] - mn); S1[c] = __builtin_amdgcn_exp2f(S1[c] - mn); ps += S0[c] + S1[c];
.LBB0_818:
	v_add_u32_e32 v0, v230, v212
	ds_read_b128 v[2:5], v0 offset:25600
	ds_read_b128 v[34:37], v0 offset:25632
	s_nop 6
	ds_read_b128 v[18:21], v0 offset:30208
	ds_read_b128 v[38:41], v0 offset:30240
	s_waitcnt lgkmcnt(3)
	v_mfma_f32_32x32x16_bf16 v[2:17], v[2:5], v[144:147], 0
	s_waitcnt lgkmcnt(1)
	v_mfma_f32_32x32x16_bf16 v[18:33], v[18:21], v[144:147], 0
	v_mfma_f32_32x32x16_bf16 v[2:17], v[34:37], v[156:159], v[2:17]
	ds_read_b128 v[34:37], v0 offset:25664
	ds_read_b128 v[42:45], v0 offset:30272
	s_waitcnt lgkmcnt(2)
	v_mfma_f32_32x32x16_bf16 v[18:33], v[38:41], v[156:159], v[18:33]
	s_waitcnt lgkmcnt(1)
	v_mfma_f32_32x32x16_bf16 v[2:17], v[34:37], v[160:163], v[2:17]
	ds_read_b128 v[34:37], v0 offset:25696
	ds_read_b128 v[38:41], v0 offset:30304
	s_waitcnt lgkmcnt(2)
	v_mfma_f32_32x32x16_bf16 v[18:33], v[42:45], v[160:163], v[18:33]
	s_waitcnt lgkmcnt(1)
	v_mfma_f32_32x32x16_bf16 v[2:17], v[34:37], v[168:171], v[2:17]
	s_mulk_i32 s74, 0x4800
	v_add_u32_e32 v66, s74, v233
	s_waitcnt lgkmcnt(0)
	v_mfma_f32_32x32x16_bf16 v[18:33], v[38:41], v[168:171], v[18:33]
	s_nop 7
	v_max_f32_e32 v0, v3, v3
	v_max_f32_e32 v34, v2, v2
	v_max_f32_e32 v0, v34, v0
	v_max3_f32 v0, v0, v4, v5
	v_max3_f32 v0, v0, v6, v7
	v_max3_f32 v0, v0, v8, v9
	v_max3_f32 v0, v0, v10, v11
	v_max3_f32 v0, v0, v12, v13
	v_max3_f32 v0, v0, v14, v15
	v_max3_f32 v0, v0, v16, v17
	v_max3_f32 v0, v0, v18, v19
	v_max3_f32 v0, v0, v20, v21
	v_max3_f32 v0, v0, v22, v23
	v_max3_f32 v0, v0, v24, v25
	v_max3_f32 v0, v0, v26, v27
	v_max3_f32 v0, v0, v28, v29
	v_max3_f32 v0, v0, v30, v31
	v_max3_f32 v0, v0, v32, v33
	ds_bpermute_b32 v50, v225, v0
	ds_read_b128 v[34:37], v66 offset:51200
	ds_read_b128 v[38:41], v66 offset:51232
	ds_read_b128 v[42:45], v66 offset:51264
	ds_read_b128 v[46:49], v66 offset:51296
	s_waitcnt lgkmcnt(4)
	v_max3_f32 v236, v235, v0, v50
	v_sub_f32_e32 v67, v236, v235
	v_cmp_lt_f32_e32 vcc, 4.0, v67
	v_cndmask_b32_e32 v236, v235, v236, vcc
	v_cmp_gt_f32_e32 vcc, v236, v235
	s_cmp_lg_u64 vcc, 0
	v_sub_f32_e32 v67, v235, v236
	s_cselect_b64 s[36:37], -1, 0
	ds_read_b128 v[50:53], v66 offset:55808
	ds_read_b128 v[54:57], v66 offset:55840
	ds_read_b128 v[58:61], v66 offset:55872
	ds_read_b128 v[62:65], v66 offset:55904
	v_sub_f32_e32 v0, v2, v236
	v_exp_f32_e32 v68, v0
	v_sub_f32_e32 v0, v18, v236
	v_exp_f32_e32 v18, v0
	s_waitcnt lgkmcnt(7)
	v_mfma_f32_32x32x16_bf16 v[80:95], v[34:37], v[164:167], v[80:95]
	v_add_f32_e32 v35, v18, v68
	v_sub_f32_e32 v0, v3, v236
	v_sub_f32_e32 v2, v19, v236
	v_exp_f32_e32 v0, v0
	v_exp_f32_e32 v34, v2
	s_waitcnt lgkmcnt(6)
	v_mfma_f32_32x32x16_bf16 v[80:95], v[38:41], v[148:151], v[80:95]
	v_add_f32_e64 v2, v34, v0
	v_add_f32_e64 v3, v35, v1
	v_add_f32_e32 v3, v2, v3
	v_cvt_pk_bf16_f32 v237, v18, v34
	v_cvt_pk_bf16_f32 v0, v68, v0
	v_sub_f32_e32 v2, v4, v236
	v_exp_f32_e32 v34, v2
	v_sub_f32_e32 v2, v20, v236
	v_exp_f32_e32 v20, v2
	s_waitcnt lgkmcnt(5)
	v_mfma_f32_32x32x16_bf16 v[80:95], v[42:45], v[172:175], v[80:95]
	v_add_f32_e32 v19, v20, v34
	v_sub_f32_e32 v2, v5, v236
	v_sub_f32_e32 v4, v21, v236
	v_exp_f32_e32 v2, v2
	v_exp_f32_e32 v18, v4
	s_waitcnt lgkmcnt(4)
	v_mfma_f32_32x32x16_bf16 v[80:95], v[46:49], v[152:155], v[80:95]
	v_cvt_pk_bf16_f32 v238, v34, v2
	v_add_f32_e64 v4, v18, v2
	v_add_f32_e64 v5, v19, v3
	v_cvt_pk_bf16_f32 v239, v20, v18
	v_add_f32_e64 v42, v4, v4
	v_add_f32_e64 v43, v4, v5
	ds_read_b128 v[2:5], v66 offset:60416
	ds_read_b128 v[18:21], v66 offset:60448
	ds_read_b128 v[34:37], v66 offset:60480
	ds_read_b128 v[38:41], v66 offset:60512
	v_sub_f32_e32 v6, v6, v236
	v_exp_f32_e32 v46, v6
	v_sub_f32_e32 v6, v22, v236
	v_exp_f32_e32 v22, v6
	s_waitcnt lgkmcnt(7)
	v_mfma_f32_32x32x16_bf16 v[96:111], v[50:53], v[164:167], v[96:111]
	v_add_f32_e32 v45, v22, v46
	v_sub_f32_e32 v6, v7, v236
	v_exp_f32_e32 v42, v6
	v_sub_f32_e32 v6, v23, v236
	v_exp_f32_e32 v44, v6
	s_waitcnt lgkmcnt(6)
	v_mfma_f32_32x32x16_bf16 v[96:111], v[54:57], v[148:151], v[96:111]
	v_cvt_pk_bf16_f32 v240, v46, v42
	v_add_f32_e64 v6, v44, v42
	v_add_f32_e64 v7, v45, v43
	v_add_f32_e32 v7, v6, v7
	v_cvt_pk_bf16_f32 v241, v22, v44
	v_sub_f32_e32 v6, v8, v236
	v_exp_f32_e32 v42, v6
	v_sub_f32_e32 v6, v24, v236
	v_exp_f32_e32 v24, v6
	s_waitcnt lgkmcnt(5)
	v_mfma_f32_32x32x16_bf16 v[96:111], v[58:61], v[172:175], v[96:111]
	v_add_f32_e32 v23, v24, v42
	v_sub_f32_e32 v6, v9, v236
	v_sub_f32_e32 v8, v25, v236
	v_exp_f32_e32 v6, v6
	v_exp_f32_e32 v22, v8
	s_waitcnt lgkmcnt(4)
; #define LAS __attribute__((address_space(3)))
; __device__ __forceinline__ unsigned pk2(float lo, float hi) { f32x2_t v = {lo, hi}; bf16x2_t b = __builtin_convertvector(v, bf16x2_t); return __builtin_bit_cast(unsigned, b); }
; #define MFMA32(a, b, c) __builtin_amdgcn_mfma_f32_32x32x16_bf16((a), (b), (c), 0, 0, 0)
; template <int DQK, int VAR> __device__ __forceinline__ void att_tile_fused(LAS unsigned char* lds, int kt, int mylast, bool& pend, int vs_prev, int vs_cur, int lane_off, int r, int h, ...
;     ...
; #pragma unroll
;     for (int db = 0; db < 4; ++db) {
;         if (db < 3) {
; #pragma unroll
;             for (int js = 0; js < 4; ++js) va[(db + 1) & 1][js] = *(const LAS bf16x8*)(vb + (db + 1) * 32 * VPB + js * 32);
;         }
; #pragma unroll
;         for (int js = 0; js < 4; ++js) {
;             const int c = db * 4 + js;
;             O[db] = MFMA32(va[db & 1][js], pf[js], O[db]);
;             S0[c] = __builtin_amdgcn_exp2f(S0[c] - mn); S1[c] = __builtin_amdgcn_exp2f(S1[c] - mn); ps += S0[c] + S1[c];
;             if (c & 1) {
;                 const unsigned a = pk2(S0[c - 1], S0[c]), b = pk2(S1[c - 1], S1[c]);
;                 const int q = c >> 1;
;                 if (q == 0) { w0.x = a; w2.x = b; } else if (q == 1) { w0.y = a; w2.y = b; } else if (q == 2) { w0.z = a; w2.z = b; } else if (q == 3) { w0.w = a; w2.w = b; }
;                 else if (q == 4) { w1.x = a; w3.x = b; } else if (q == 5) { w1.y = a; w3.y = b; } else if (q == 6) { w1.z = a; w3.z = b; } else { w1.w = a; w3.w = b; }
;             }
;             __builtin_amdgcn_sched_barrier(0);
;         }
;     }
;     lrun = lrun * alpha + ps;
;     alpha_p = alpha; grew_p = grew;
;     pf[0] = __builtin_bit_cast(bf16x8, w0); pf[1] = __builtin_bit_cast(bf16x8, w1); pf[2] = __builtin_bit_cast(bf16x8, w2); pf[3] = __builtin_bit_cast(bf16x8, w3);
;     pend = true;
	v_mfma_f32_32x32x16_bf16 v[96:111], v[62:65], v[152:155], v[96:111]
	v_cvt_pk_bf16_f32 v242, v42, v6
	v_add_f32_e64 v8, v22, v6
	v_add_f32_e64 v9, v23, v7
	v_cvt_pk_bf16_f32 v243, v24, v22
	v_add_f32_e64 v50, v8, v8
	v_add_f32_e64 v51, v8, v9
	ds_read_b128 v[6:9], v66 offset:65024
	ds_read_b128 v[22:25], v66 offset:65056
	ds_read_b128 v[42:45], v66 offset:65088
	ds_read_b128 v[46:49], v66 offset:65120
	v_sub_f32_e32 v10, v10, v236
	v_sub_f32_e32 v26, v26, v236
	v_exp_f32_e32 v10, v10
	v_exp_f32_e32 v26, v26
	s_waitcnt lgkmcnt(7)
	v_mfma_f32_32x32x16_bf16 v[112:127], v[2:5], v[164:167], v[112:127]
	v_add_f32_e32 v3, v26, v10
	v_sub_f32_e32 v2, v11, v236
	v_exp_f32_e32 v50, v2
	v_sub_f32_e32 v2, v27, v236
	v_exp_f32_e32 v2, v2
	s_waitcnt lgkmcnt(6)
	v_mfma_f32_32x32x16_bf16 v[112:127], v[18:21], v[148:151], v[112:127]
	v_cvt_pk_bf16_f32 v244, v10, v50
	v_add_f32_e64 v4, v2, v50
	v_add_f32_e64 v5, v3, v51
	v_add_f32_e32 v5, v4, v5
	v_cvt_pk_bf16_f32 v245, v26, v2
	v_sub_f32_e32 v2, v12, v236
	v_exp_f32_e32 v12, v2
	v_sub_f32_e32 v2, v28, v236
	v_exp_f32_e32 v18, v2
	s_waitcnt lgkmcnt(5)
	v_mfma_f32_32x32x16_bf16 v[112:127], v[34:37], v[172:175], v[112:127]
	v_add_f32_e32 v3, v18, v12
	v_sub_f32_e32 v2, v13, v236
	v_exp_f32_e32 v4, v2
	v_sub_f32_e32 v2, v29, v236
	v_exp_f32_e32 v2, v2
	s_waitcnt lgkmcnt(4)
	v_mfma_f32_32x32x16_bf16 v[112:127], v[38:41], v[152:155], v[112:127]
	v_cvt_pk_bf16_f32 v12, v12, v4
	v_add_f32_e64 v10, v2, v4
	v_add_f32_e64 v11, v3, v5
	v_add_f32_e32 v11, v10, v11
	v_cvt_pk_bf16_f32 v13, v18, v2
	v_sub_f32_e32 v2, v14, v236
	v_exp_f32_e32 v14, v2
	v_sub_f32_e32 v2, v30, v236
	v_exp_f32_e32 v18, v2
	s_waitcnt lgkmcnt(3)
	v_mfma_f32_32x32x16_bf16 v[128:143], v[6:9], v[164:167], v[128:143]
	v_add_f32_e32 v3, v18, v14
	v_sub_f32_e32 v2, v15, v236
	v_exp_f32_e32 v10, v2
	v_sub_f32_e32 v2, v31, v236
	v_exp_f32_e32 v2, v2
	s_waitcnt lgkmcnt(2)
	v_mfma_f32_32x32x16_bf16 v[128:143], v[22:25], v[148:151], v[128:143]
	v_cvt_pk_bf16_f32 v150, v14, v10
	v_add_f32_e64 v4, v2, v10
	v_add_f32_e64 v5, v3, v11
	v_add_f32_e32 v5, v4, v5
	v_cvt_pk_bf16_f32 v8, v18, v2
	v_sub_f32_e32 v2, v16, v236
	v_exp_f32_e32 v9, v2
	v_sub_f32_e32 v2, v32, v236
	v_exp_f32_e32 v10, v2
	s_waitcnt lgkmcnt(1)
	v_mfma_f32_32x32x16_bf16 v[128:143], v[42:45], v[172:175], v[128:143]
	v_add_f32_e32 v3, v10, v9
	v_sub_f32_e32 v2, v17, v236
	v_exp_f32_e32 v4, v2
	v_sub_f32_e32 v2, v33, v236
	v_exp_f32_e32 v2, v2
	s_waitcnt lgkmcnt(0)
	v_mfma_f32_32x32x16_bf16 v[128:143], v[46:49], v[152:155], v[128:143]
	v_cvt_pk_bf16_f32 v151, v9, v4
	v_add_f32_e64 v6, v2, v4
	v_add_f32_e64 v7, v3, v5
	v_cvt_pk_bf16_f32 v155, v10, v2
	v_add_f32_e32 v3, v6, v7
	v_exp_f32_e32 v224, v67
	s_nop 5
	v_mov_b64_e32 v[16:17], v[128:129]
	v_mov_b64_e32 v[48:49], v[112:113]
	v_mov_b64_e32 v[64:65], v[96:97]
	v_fmac_f32_e32 v3, v211, v224
	v_mov_b64_e32 v[32:33], v[80:81]
	v_mov_b64_e32 v[18:19], v[130:131]
	v_mov_b64_e32 v[20:21], v[132:133]
	v_mov_b64_e32 v[22:23], v[134:135]
	v_mov_b64_e32 v[24:25], v[136:137]
	v_mov_b64_e32 v[26:27], v[138:139]
	v_mov_b64_e32 v[28:29], v[140:141]
	v_mov_b64_e32 v[30:31], v[142:143]
	v_mov_b64_e32 v[50:51], v[114:115]
	v_mov_b64_e32 v[52:53], v[116:117]
	v_mov_b64_e32 v[54:55], v[118:119]
	v_mov_b64_e32 v[56:57], v[120:121]
	v_mov_b64_e32 v[58:59], v[122:123]
	v_mov_b64_e32 v[60:61], v[124:125]
	v_mov_b64_e32 v[62:63], v[126:127]
	v_mov_b64_e32 v[66:67], v[98:99]
	v_mov_b64_e32 v[68:69], v[100:101]
	v_mov_b64_e32 v[70:71], v[102:103]
	v_mov_b64_e32 v[72:73], v[104:105]
	v_mov_b64_e32 v[74:75], v[106:107]
	v_mov_b64_e32 v[76:77], v[108:109]
	v_mov_b64_e32 v[78:79], v[110:111]
	v_mov_b64_e32 v[34:35], v[82:83]
	v_mov_b64_e32 v[36:37], v[84:85]
	v_mov_b64_e32 v[38:39], v[86:87]
	v_mov_b64_e32 v[40:41], v[88:89]
	v_mov_b64_e32 v[42:43], v[90:91]
	v_mov_b64_e32 v[44:45], v[92:93]
	v_mov_b64_e32 v[46:47], v[94:95]
	v_mov_b32_e32 v235, v236
	v_mov_b32_e32 v211, v3
	v_mov_b32_e32 v164, v0
	v_mov_b32_e32 v165, v238
	v_mov_b32_e32 v166, v240
	v_mov_b32_e32 v167, v242
	v_mov_b32_e32 v148, v244
	v_mov_b32_e32 v149, v12
	v_mov_b32_e32 v172, v237
	v_mov_b32_e32 v173, v239
	v_mov_b32_e32 v174, v241
	v_mov_b32_e32 v175, v243
	v_mov_b32_e32 v152, v245
	v_mov_b32_e32 v153, v13
	v_mov_b32_e32 v154, v8
	s_andn2_b64 vcc, exec, s[30:31]
	s_cbranch_vccz .LBB0_811
	s_branch .LBB0_812

; #define LAS __attribute__((address_space(3)))
; #define MFMA32(a, b, c) __builtin_amdgcn_mfma_f32_32x32x16_bf16((a), (b), (c), 0, 0, 0)
; template <int DQK, int VAR> __device__ __forceinline__ void att_tile_fused(LAS unsigned char* lds, int kt, int mylast, bool& pend, int vs_prev, int vs_cur, int lane_off, int r, int h, ...
;     ...
;     f32x16 S0, S1;
; #pragma unroll
;     for (int i = 0; i < 16; ++i) { S0[i] = 0.f; S1[i] = 0.f; }
;     const LAS unsigned char* kb = lds + (kt & 1) * ATT_KBYTES + r * KP + h * 16;
;     bf16x8 ka[2][2];
;     ka[0][0] = *(const LAS bf16x8*)(kb); ka[0][1] = *(const LAS bf16x8*)(kb + 32 * KP);
; #pragma unroll
;     for (int s = 0; s < NS; ++s) {
;         if (s + 1 < NS) { ka[(s + 1) & 1][0] = *(const LAS bf16x8*)(kb + (s + 1) * 32); ka[(s + 1) & 1][1] = *(const LAS bf16x8*)(kb + 32 * KP + (s + 1) * 32); }
;         S0 = MFMA32(ka[s & 1][0], qf[s], S0); S1 = MFMA32(ka[s & 1][1], qf[s], S1);
;         __builtin_amdgcn_sched_barrier(0);
;     }
;     const LAS unsigned char* vb = lds + ATT_VOFF + (pend ? vs_prev : vs_cur) * ATT_VBYTES + lane_off;
;     bf16x8 va[2][4];
; #pragma unroll
;     for (int js = 0; js < 4; ++js) va[0][js] = *(const LAS bf16x8*)(vb + js * 32);
;     float mx = S0[0];
; #pragma unroll
;     for (int i = 1; i < 16; ++i) mx = fmaxf(mx, S0[i]);
; #pragma unroll
;     for (int i = 0; i < 16; ++i) mx = fmaxf(mx, S1[i]);
;     mx = fmaxf(mx, __shfl_xor(mx, 32));
;     const float mn = fmaxf(mrun, mx), alpha = __builtin_amdgcn_exp2f(mrun - mn);
;     const bool grew = __builtin_amdgcn_ballot_w64(mn > mrun) != 0ull;
;     mrun = mn;
;     float ps = 0.f;
;     u32x4 w0, w1, w2, w3;
;     __builtin_amdgcn_sched_barrier(0);
; #pragma unroll
;     for (int db = 0; db < 4; ++db) {
;         if (db < 3) {
; #pragma unroll
;             for (int js = 0; js < 4; ++js) va[(db + 1) & 1][js] = *(const LAS bf16x8*)(vb + (db + 1) * 32 * VPB + js * 32);
;         }
; #pragma unroll
;         for (int js = 0; js < 4; ++js) {
;             const int c = db * 4 + js;
;             O[db] = MFMA32(va[db & 1][js], pf[js], O[db]);
;             S0[c] = __builtin_amdgcn_exp2f(S0[c] - mn); S1[c] = __builtin_amdgcn_exp2f(S1[c] - mn); ps += S0[c] + S1[c];
.LBB0_841:
	s_andn2_b64 vcc, exec, s[30:31]
	s_mov_b64 s[30:31], 0
	s_cbranch_vccnz .LBB0_843
	v_add_u32_e32 v0, v211, v186
	ds_read_b128 v[66:69], v0
	ds_read_b128 v[98:101], v0 offset:32
	ds_read_b128 v[82:85], v0 offset:4608
	ds_read_b128 v[102:105], v0 offset:4640
	s_waitcnt lgkmcnt(3)
	v_mfma_f32_32x32x16_bf16 v[66:81], v[66:69], v[138:141], 0
	s_waitcnt lgkmcnt(1)
	v_mfma_f32_32x32x16_bf16 v[82:97], v[82:85], v[138:141], 0
	v_mfma_f32_32x32x16_bf16 v[66:81], v[98:101], v[142:145], v[66:81]
	ds_read_b128 v[98:101], v0 offset:64
	ds_read_b128 v[106:109], v0 offset:4672
	s_waitcnt lgkmcnt(2)
	v_mfma_f32_32x32x16_bf16 v[82:97], v[102:105], v[142:145], v[82:97]
	s_waitcnt lgkmcnt(1)
	v_mfma_f32_32x32x16_bf16 v[66:81], v[98:101], v[150:153], v[66:81]
	ds_read_b128 v[98:101], v0 offset:96
	ds_read_b128 v[102:105], v0 offset:4704
	s_waitcnt lgkmcnt(2)
	v_mfma_f32_32x32x16_bf16 v[82:97], v[106:109], v[150:153], v[82:97]
	s_waitcnt lgkmcnt(1)
	v_mfma_f32_32x32x16_bf16 v[66:81], v[98:101], v[158:161], v[66:81]
	s_and_b64 s[28:29], s[28:29], exec
	s_cselect_b32 s14, s25, s37
	s_mulk_i32 s14, 0x4800
	v_add_u32_e32 v198, s14, v214
	s_waitcnt lgkmcnt(0)
	v_mfma_f32_32x32x16_bf16 v[82:97], v[102:105], v[158:161], v[82:97]
	s_nop 5
	v_max_f32_e32 v0, v67, v67
	v_max_f32_e32 v98, v66, v66
	v_max_f32_e32 v0, v98, v0
	v_max3_f32 v0, v0, v68, v69
	v_max3_f32 v0, v0, v70, v71
	v_max3_f32 v0, v0, v72, v73
	v_max3_f32 v0, v0, v74, v75
	v_max3_f32 v0, v0, v76, v77
	v_max3_f32 v0, v0, v78, v79
	v_max3_f32 v0, v0, v80, v81
	v_max3_f32 v0, v0, v82, v83
	v_max3_f32 v0, v0, v84, v85
	v_max3_f32 v0, v0, v86, v87
	v_max3_f32 v0, v0, v88, v89
	v_max3_f32 v0, v0, v90, v91
	v_max3_f32 v0, v0, v92, v93
	v_max3_f32 v0, v0, v94, v95
	v_max3_f32 v0, v0, v96, v97
	ds_bpermute_b32 v114, v225, v0
	ds_read_b128 v[98:101], v198 offset:51200
	ds_read_b128 v[102:105], v198 offset:51232
	ds_read_b128 v[106:109], v198 offset:51264
	ds_read_b128 v[110:113], v198 offset:51296
	s_waitcnt lgkmcnt(4)
	v_max3_f32 v217, v216, v0, v114
	v_sub_f32_e32 v218, v217, v216
	v_cmp_lt_f32_e32 vcc, 4.0, v218
	v_cndmask_b32_e32 v217, v216, v217, vcc
	v_cmp_gt_f32_e32 vcc, v217, v216
	s_cmp_lg_u64 vcc, 0
	s_cselect_b64 s[30:31], -1, 0
	v_sub_f32_e32 v218, v216, v217
	ds_read_b128 v[114:117], v198 offset:55808
	ds_read_b128 v[118:121], v198 offset:55840
	ds_read_b128 v[122:125], v198 offset:55872
	ds_read_b128 v[126:129], v198 offset:55904
	v_sub_f32_e32 v0, v66, v217
	v_exp_f32_e32 v216, v0
	v_sub_f32_e32 v0, v82, v217
	v_exp_f32_e32 v82, v0
	s_waitcnt lgkmcnt(7)
	v_mfma_f32_32x32x16_bf16 v[2:17], v[98:101], v[146:149], v[2:17]
	v_add_f32_e32 v99, v82, v216
	v_sub_f32_e32 v0, v67, v217
	v_sub_f32_e32 v66, v83, v217
	v_exp_f32_e32 v0, v0
	v_exp_f32_e32 v98, v66
	s_waitcnt lgkmcnt(6)
	v_mfma_f32_32x32x16_bf16 v[2:17], v[102:105], v[130:133], v[2:17]
	v_add_f32_e64 v66, v98, v0
	v_add_f32_e64 v67, v99, v1
	v_add_f32_e32 v67, v66, v67
	v_cvt_pk_bf16_f32 v219, v82, v98
	v_cvt_pk_bf16_f32 v0, v216, v0
	v_sub_f32_e32 v66, v68, v217
	v_exp_f32_e32 v98, v66
	v_sub_f32_e32 v66, v84, v217
	v_exp_f32_e32 v84, v66
	s_waitcnt lgkmcnt(5)
	v_mfma_f32_32x32x16_bf16 v[2:17], v[106:109], v[154:157], v[2:17]
	v_add_f32_e32 v83, v84, v98
	v_sub_f32_e32 v66, v69, v217
	v_sub_f32_e32 v68, v85, v217
	v_exp_f32_e32 v66, v66
	v_exp_f32_e32 v82, v68
	s_waitcnt lgkmcnt(4)
	v_mfma_f32_32x32x16_bf16 v[2:17], v[110:113], v[134:137], v[2:17]
	v_cvt_pk_bf16_f32 v220, v98, v66
	v_add_f32_e64 v68, v82, v66
	v_add_f32_e64 v69, v83, v67
	v_cvt_pk_bf16_f32 v221, v84, v82
	v_add_f32_e64 v106, v68, v68
	v_add_f32_e64 v107, v68, v69
	ds_read_b128 v[66:69], v198 offset:60416
	ds_read_b128 v[82:85], v198 offset:60448
	ds_read_b128 v[98:101], v198 offset:60480
	ds_read_b128 v[102:105], v198 offset:60512
	v_sub_f32_e32 v70, v70, v217
	v_exp_f32_e32 v110, v70
	v_sub_f32_e32 v70, v86, v217
	v_exp_f32_e32 v86, v70
	s_waitcnt lgkmcnt(7)
	v_mfma_f32_32x32x16_bf16 v[18:33], v[114:117], v[146:149], v[18:33]
	v_add_f32_e32 v109, v86, v110
	v_sub_f32_e32 v70, v71, v217
	v_exp_f32_e32 v106, v70
	v_sub_f32_e32 v70, v87, v217
	v_exp_f32_e32 v108, v70
	s_waitcnt lgkmcnt(6)
	v_mfma_f32_32x32x16_bf16 v[18:33], v[118:121], v[130:133], v[18:33]
	v_cvt_pk_bf16_f32 v222, v110, v106
	v_add_f32_e64 v70, v108, v106
	v_add_f32_e64 v71, v109, v107
	v_add_f32_e32 v71, v70, v71
	v_cvt_pk_bf16_f32 v223, v86, v108
	v_sub_f32_e32 v70, v72, v217
	v_exp_f32_e32 v106, v70
	v_sub_f32_e32 v70, v88, v217
	v_exp_f32_e32 v88, v70
	s_waitcnt lgkmcnt(5)
; #define LAS __attribute__((address_space(3)))
; __device__ __forceinline__ unsigned pk2(float lo, float hi) { f32x2_t v = {lo, hi}; bf16x2_t b = __builtin_convertvector(v, bf16x2_t); return __builtin_bit_cast(unsigned, b); }
; #define MFMA32(a, b, c) __builtin_amdgcn_mfma_f32_32x32x16_bf16((a), (b), (c), 0, 0, 0)
; template <int DQK, int VAR> __device__ __forceinline__ void att_tile_fused(LAS unsigned char* lds, int kt, int mylast, bool& pend, int vs_prev, int vs_cur, int lane_off, int r, int h, ...
;     ...
; #pragma unroll
;     for (int db = 0; db < 4; ++db) {
;         if (db < 3) {
; #pragma unroll
;             for (int js = 0; js < 4; ++js) va[(db + 1) & 1][js] = *(const LAS bf16x8*)(vb + (db + 1) * 32 * VPB + js * 32);
;         }
; #pragma unroll
;         for (int js = 0; js < 4; ++js) {
;             const int c = db * 4 + js;
;             O[db] = MFMA32(va[db & 1][js], pf[js], O[db]);
;             S0[c] = __builtin_amdgcn_exp2f(S0[c] - mn); S1[c] = __builtin_amdgcn_exp2f(S1[c] - mn); ps += S0[c] + S1[c];
;             if (c & 1) {
;                 const unsigned a = pk2(S0[c - 1], S0[c]), b = pk2(S1[c - 1], S1[c]);
;                 const int q = c >> 1;
;                 if (q == 0) { w0.x = a; w2.x = b; } else if (q == 1) { w0.y = a; w2.y = b; } else if (q == 2) { w0.z = a; w2.z = b; } else if (q == 3) { w0.w = a; w2.w = b; }
;                 else if (q == 4) { w1.x = a; w3.x = b; } else if (q == 5) { w1.y = a; w3.y = b; } else if (q == 6) { w1.z = a; w3.z = b; } else { w1.w = a; w3.w = b; }
;             }
;             __builtin_amdgcn_sched_barrier(0);
;         }
;     }
;     lrun = lrun * alpha + ps;
;     alpha_p = alpha; grew_p = grew;
;     pf[0] = __builtin_bit_cast(bf16x8, w0); pf[1] = __builtin_bit_cast(bf16x8, w1); pf[2] = __builtin_bit_cast(bf16x8, w2); pf[3] = __builtin_bit_cast(bf16x8, w3);
;     pend = true;
	v_mfma_f32_32x32x16_bf16 v[18:33], v[122:125], v[154:157], v[18:33]
	v_add_f32_e32 v87, v88, v106
	v_sub_f32_e32 v70, v73, v217
	v_sub_f32_e32 v72, v89, v217
	v_exp_f32_e32 v70, v70
	v_exp_f32_e32 v86, v72
	s_waitcnt lgkmcnt(4)
	v_mfma_f32_32x32x16_bf16 v[18:33], v[126:129], v[134:137], v[18:33]
	v_cvt_pk_bf16_f32 v224, v106, v70
	v_add_f32_e64 v72, v86, v70
	v_add_f32_e64 v73, v87, v71
	v_cvt_pk_bf16_f32 v230, v88, v86
	v_add_f32_e64 v114, v72, v72
	v_add_f32_e64 v115, v72, v73
	ds_read_b128 v[70:73], v198 offset:65024
	ds_read_b128 v[86:89], v198 offset:65056
	ds_read_b128 v[106:109], v198 offset:65088
	ds_read_b128 v[110:113], v198 offset:65120
	v_sub_f32_e32 v74, v74, v217
	v_sub_f32_e32 v90, v90, v217
	v_exp_f32_e32 v74, v74
	v_exp_f32_e32 v90, v90
	s_waitcnt lgkmcnt(7)
	v_mfma_f32_32x32x16_bf16 v[34:49], v[66:69], v[146:149], v[34:49]
	v_add_f32_e32 v67, v90, v74
	v_sub_f32_e32 v66, v75, v217
	v_exp_f32_e32 v114, v66
	v_sub_f32_e32 v66, v91, v217
	v_exp_f32_e32 v66, v66
	s_waitcnt lgkmcnt(6)
	v_mfma_f32_32x32x16_bf16 v[34:49], v[82:85], v[130:133], v[34:49]
	v_cvt_pk_bf16_f32 v231, v74, v114
	v_add_f32_e64 v68, v66, v114
	v_add_f32_e64 v69, v67, v115
	v_add_f32_e32 v69, v68, v69
	v_cvt_pk_bf16_f32 v232, v90, v66
	v_sub_f32_e32 v66, v76, v217
	v_exp_f32_e32 v76, v66
	v_sub_f32_e32 v66, v92, v217
	v_exp_f32_e32 v82, v66
	s_waitcnt lgkmcnt(5)
	v_mfma_f32_32x32x16_bf16 v[34:49], v[98:101], v[154:157], v[34:49]
	v_add_f32_e32 v67, v82, v76
	v_sub_f32_e32 v66, v77, v217
	v_exp_f32_e32 v68, v66
	v_sub_f32_e32 v66, v93, v217
	v_exp_f32_e32 v66, v66
	s_waitcnt lgkmcnt(4)
	v_mfma_f32_32x32x16_bf16 v[34:49], v[102:105], v[134:137], v[34:49]
	v_cvt_pk_bf16_f32 v233, v76, v68
	v_add_f32_e64 v74, v66, v68
	v_add_f32_e64 v75, v67, v69
	v_add_f32_e32 v75, v74, v75
	v_cvt_pk_bf16_f32 v234, v82, v66
	v_sub_f32_e32 v66, v78, v217
	v_exp_f32_e32 v76, v66
	v_sub_f32_e32 v66, v94, v217
	v_exp_f32_e32 v77, v66
	s_waitcnt lgkmcnt(3)
	v_mfma_f32_32x32x16_bf16 v[50:65], v[70:73], v[146:149], v[50:65]
	v_add_f32_e32 v67, v77, v76
	v_sub_f32_e32 v66, v79, v217
	v_exp_f32_e32 v74, v66
	v_sub_f32_e32 v66, v95, v217
	v_exp_f32_e32 v66, v66
	s_waitcnt lgkmcnt(2)
	v_mfma_f32_32x32x16_bf16 v[50:65], v[86:89], v[130:133], v[50:65]
	v_cvt_pk_bf16_f32 v132, v76, v74
	v_add_f32_e64 v68, v66, v74
	v_add_f32_e64 v69, v67, v75
	v_add_f32_e32 v69, v68, v69
	v_cvt_pk_bf16_f32 v235, v77, v66
	v_sub_f32_e32 v66, v80, v217
	v_exp_f32_e32 v72, v66
	v_sub_f32_e32 v66, v96, v217
	v_exp_f32_e32 v73, v66
	s_waitcnt lgkmcnt(1)
	v_mfma_f32_32x32x16_bf16 v[50:65], v[106:109], v[154:157], v[50:65]
	v_add_f32_e32 v67, v73, v72
	v_sub_f32_e32 v66, v81, v217
	v_exp_f32_e32 v68, v66
	v_sub_f32_e32 v66, v97, v217
	v_exp_f32_e32 v66, v66
	s_waitcnt lgkmcnt(0)
	v_mfma_f32_32x32x16_bf16 v[50:65], v[110:113], v[134:137], v[50:65]
	v_cvt_pk_bf16_f32 v133, v72, v68
	v_add_f32_e64 v70, v66, v68
	v_add_f32_e64 v71, v67, v69
	v_add_f32_e32 v130, v70, v71
	v_cvt_pk_bf16_f32 v137, v73, v66
	v_exp_f32_e32 v198, v218
	s_nop 5
	v_mov_b64_e32 v[128:129], v[64:65]
	v_mov_b64_e32 v[112:113], v[48:49]
	v_mov_b64_e32 v[96:97], v[32:33]
	v_fmac_f32_e32 v130, v187, v198
	v_mov_b64_e32 v[80:81], v[16:17]
	v_mov_b64_e32 v[126:127], v[62:63]
	v_mov_b64_e32 v[124:125], v[60:61]
	v_mov_b64_e32 v[122:123], v[58:59]
	v_mov_b64_e32 v[120:121], v[56:57]
	v_mov_b64_e32 v[118:119], v[54:55]
	v_mov_b64_e32 v[116:117], v[52:53]
	v_mov_b64_e32 v[114:115], v[50:51]
	v_mov_b64_e32 v[110:111], v[46:47]
	v_mov_b64_e32 v[108:109], v[44:45]
	v_mov_b64_e32 v[106:107], v[42:43]
	v_mov_b64_e32 v[104:105], v[40:41]
	v_mov_b64_e32 v[102:103], v[38:39]
	v_mov_b64_e32 v[100:101], v[36:37]
	v_mov_b64_e32 v[98:99], v[34:35]
	v_mov_b64_e32 v[94:95], v[30:31]
	v_mov_b64_e32 v[92:93], v[28:29]
	v_mov_b64_e32 v[90:91], v[26:27]
	v_mov_b64_e32 v[88:89], v[24:25]
	v_mov_b64_e32 v[86:87], v[22:23]
	v_mov_b64_e32 v[84:85], v[20:21]
	v_mov_b64_e32 v[82:83], v[18:19]
	v_mov_b64_e32 v[78:79], v[14:15]
	v_mov_b64_e32 v[76:77], v[12:13]
	v_mov_b64_e32 v[74:75], v[10:11]
	v_mov_b64_e32 v[72:73], v[8:9]
	v_mov_b64_e32 v[70:71], v[6:7]
	v_mov_b64_e32 v[68:69], v[4:5]
	v_mov_b64_e32 v[66:67], v[2:3]
	v_mov_b32_e32 v216, v217
	v_mov_b32_e32 v187, v130
	v_mov_b32_e32 v146, v0
	v_mov_b32_e32 v147, v220
	v_mov_b32_e32 v148, v222
	v_mov_b32_e32 v149, v224
	v_mov_b32_e32 v130, v231
	v_mov_b32_e32 v131, v233
	v_mov_b32_e32 v154, v219
	v_mov_b32_e32 v155, v221
	v_mov_b32_e32 v156, v223
	v_mov_b32_e32 v157, v230
	v_mov_b32_e32 v134, v232
	v_mov_b32_e32 v135, v234
	v_mov_b32_e32 v136, v235

; #define LAS __attribute__((address_space(3)))
; #define MFMA32(a, b, c) __builtin_amdgcn_mfma_f32_32x32x16_bf16((a), (b), (c), 0, 0, 0)
; template <int DQK, int VAR> __device__ __forceinline__ void att_tile_fused(LAS unsigned char* lds, int kt, int mylast, bool& pend, int vs_prev, int vs_cur, int lane_off, int r, int h, ...
;     ...
;     f32x16 S0, S1;
; #pragma unroll
;     for (int i = 0; i < 16; ++i) { S0[i] = 0.f; S1[i] = 0.f; }
;     const LAS unsigned char* kb = lds + (kt & 1) * ATT_KBYTES + r * KP + h * 16;
;     bf16x8 ka[2][2];
;     ka[0][0] = *(const LAS bf16x8*)(kb); ka[0][1] = *(const LAS bf16x8*)(kb + 32 * KP);
; #pragma unroll
;     for (int s = 0; s < NS; ++s) {
;         if (s + 1 < NS) { ka[(s + 1) & 1][0] = *(const LAS bf16x8*)(kb + (s + 1) * 32); ka[(s + 1) & 1][1] = *(const LAS bf16x8*)(kb + 32 * KP + (s + 1) * 32); }
;         S0 = MFMA32(ka[s & 1][0], qf[s], S0); S1 = MFMA32(ka[s & 1][1], qf[s], S1);
;         __builtin_amdgcn_sched_barrier(0);
;     }
;     const LAS unsigned char* vb = lds + ATT_VOFF + (pend ? vs_prev : vs_cur) * ATT_VBYTES + lane_off;
;     bf16x8 va[2][4];
; #pragma unroll
;     for (int js = 0; js < 4; ++js) va[0][js] = *(const LAS bf16x8*)(vb + js * 32);
;     float mx = S0[0];
; #pragma unroll
;     for (int i = 1; i < 16; ++i) mx = fmaxf(mx, S0[i]);
; #pragma unroll
;     for (int i = 0; i < 16; ++i) mx = fmaxf(mx, S1[i]);
;     mx = fmaxf(mx, __shfl_xor(mx, 32));
;     const float mn = fmaxf(mrun, mx), alpha = __builtin_amdgcn_exp2f(mrun - mn);
;     const bool grew = __builtin_amdgcn_ballot_w64(mn > mrun) != 0ull;
;     mrun = mn;
;     float ps = 0.f;
;     u32x4 w0, w1, w2, w3;
;     __builtin_amdgcn_sched_barrier(0);
; #pragma unroll
;     for (int db = 0; db < 4; ++db) {
;         if (db < 3) {
; #pragma unroll
;             for (int js = 0; js < 4; ++js) va[(db + 1) & 1][js] = *(const LAS bf16x8*)(vb + (db + 1) * 32 * VPB + js * 32);
;         }
; #pragma unroll
;         for (int js = 0; js < 4; ++js) {
;             const int c = db * 4 + js;
;             O[db] = MFMA32(va[db & 1][js], pf[js], O[db]);
;             S0[c] = __builtin_amdgcn_exp2f(S0[c] - mn); S1[c] = __builtin_amdgcn_exp2f(S1[c] - mn); ps += S0[c] + S1[c];
.LBB0_860:
	v_add_u32_e32 v0, v211, v186
	ds_read_b128 v[2:5], v0 offset:25600
	ds_read_b128 v[34:37], v0 offset:25632
	ds_read_b128 v[18:21], v0 offset:30208
	ds_read_b128 v[38:41], v0 offset:30240
	s_waitcnt lgkmcnt(3)
	v_mfma_f32_32x32x16_bf16 v[2:17], v[2:5], v[138:141], 0
	s_waitcnt lgkmcnt(1)
	v_mfma_f32_32x32x16_bf16 v[18:33], v[18:21], v[138:141], 0
	v_mfma_f32_32x32x16_bf16 v[2:17], v[34:37], v[142:145], v[2:17]
	ds_read_b128 v[34:37], v0 offset:25664
	ds_read_b128 v[42:45], v0 offset:30272
	s_waitcnt lgkmcnt(2)
	v_mfma_f32_32x32x16_bf16 v[18:33], v[38:41], v[142:145], v[18:33]
	s_waitcnt lgkmcnt(1)
	v_mfma_f32_32x32x16_bf16 v[2:17], v[34:37], v[150:153], v[2:17]
	ds_read_b128 v[34:37], v0 offset:25696
	ds_read_b128 v[38:41], v0 offset:30304
	s_waitcnt lgkmcnt(2)
	v_mfma_f32_32x32x16_bf16 v[18:33], v[42:45], v[150:153], v[18:33]
	s_waitcnt lgkmcnt(1)
	v_mfma_f32_32x32x16_bf16 v[2:17], v[34:37], v[158:161], v[2:17]
	s_mulk_i32 s37, 0x4800
	v_add_u32_e32 v198, s37, v214
	s_waitcnt lgkmcnt(0)
	v_mfma_f32_32x32x16_bf16 v[18:33], v[38:41], v[158:161], v[18:33]
	s_nop 7
	v_max_f32_e32 v0, v3, v3
	v_max_f32_e32 v34, v2, v2
	v_max_f32_e32 v0, v34, v0
	v_max3_f32 v0, v0, v4, v5
	v_max3_f32 v0, v0, v6, v7
	v_max3_f32 v0, v0, v8, v9
	v_max3_f32 v0, v0, v10, v11
	v_max3_f32 v0, v0, v12, v13
	v_max3_f32 v0, v0, v14, v15
	v_max3_f32 v0, v0, v16, v17
	v_max3_f32 v0, v0, v18, v19
	v_max3_f32 v0, v0, v20, v21
	v_max3_f32 v0, v0, v22, v23
	v_max3_f32 v0, v0, v24, v25
	v_max3_f32 v0, v0, v26, v27
	v_max3_f32 v0, v0, v28, v29
	v_max3_f32 v0, v0, v30, v31
	v_max3_f32 v0, v0, v32, v33
	ds_bpermute_b32 v50, v225, v0
	ds_read_b128 v[34:37], v198 offset:51200
	ds_read_b128 v[38:41], v198 offset:51232
	ds_read_b128 v[42:45], v198 offset:51264
	ds_read_b128 v[46:49], v198 offset:51296
	s_waitcnt lgkmcnt(4)
	v_max3_f32 v217, v216, v0, v50
	v_sub_f32_e32 v218, v217, v216
	v_cmp_lt_f32_e32 vcc, 4.0, v218
	v_cndmask_b32_e32 v217, v216, v217, vcc
	v_cmp_gt_f32_e32 vcc, v217, v216
	s_cmp_lg_u64 vcc, 0
	s_cselect_b64 s[30:31], -1, 0
	v_sub_f32_e32 v218, v216, v217
	ds_read_b128 v[50:53], v198 offset:55808
	ds_read_b128 v[54:57], v198 offset:55840
	ds_read_b128 v[58:61], v198 offset:55872
	ds_read_b128 v[62:65], v198 offset:55904
	v_sub_f32_e32 v0, v2, v217
	v_exp_f32_e32 v216, v0
	v_sub_f32_e32 v0, v18, v217
	v_exp_f32_e32 v18, v0
	s_waitcnt lgkmcnt(7)
	v_mfma_f32_32x32x16_bf16 v[66:81], v[34:37], v[146:149], v[66:81]
	v_add_f32_e32 v35, v18, v216
	v_sub_f32_e32 v0, v3, v217
	v_sub_f32_e32 v2, v19, v217
	v_exp_f32_e32 v0, v0
	v_exp_f32_e32 v34, v2
	s_waitcnt lgkmcnt(6)
	v_mfma_f32_32x32x16_bf16 v[66:81], v[38:41], v[130:133], v[66:81]
	v_add_f32_e64 v2, v34, v0
	v_add_f32_e64 v3, v35, v1
	v_add_f32_e32 v3, v2, v3
	v_cvt_pk_bf16_f32 v219, v18, v34
	v_cvt_pk_bf16_f32 v0, v216, v0
	v_sub_f32_e32 v2, v4, v217
	v_exp_f32_e32 v34, v2
	v_sub_f32_e32 v2, v20, v217
	v_exp_f32_e32 v20, v2
	s_waitcnt lgkmcnt(5)
	v_mfma_f32_32x32x16_bf16 v[66:81], v[42:45], v[154:157], v[66:81]
	v_add_f32_e32 v19, v20, v34
	v_sub_f32_e32 v2, v5, v217
	v_sub_f32_e32 v4, v21, v217
	v_exp_f32_e32 v2, v2
	v_exp_f32_e32 v18, v4
	s_waitcnt lgkmcnt(4)
	v_mfma_f32_32x32x16_bf16 v[66:81], v[46:49], v[134:137], v[66:81]
	v_cvt_pk_bf16_f32 v220, v34, v2
	v_add_f32_e64 v4, v18, v2
	v_add_f32_e64 v5, v19, v3
	v_cvt_pk_bf16_f32 v221, v20, v18
	v_add_f32_e64 v42, v4, v4
	v_add_f32_e64 v43, v4, v5
	ds_read_b128 v[2:5], v198 offset:60416
	ds_read_b128 v[18:21], v198 offset:60448
	ds_read_b128 v[34:37], v198 offset:60480
	ds_read_b128 v[38:41], v198 offset:60512
	v_sub_f32_e32 v6, v6, v217
	v_exp_f32_e32 v46, v6
	v_sub_f32_e32 v6, v22, v217
	v_exp_f32_e32 v22, v6
	s_waitcnt lgkmcnt(7)
	v_mfma_f32_32x32x16_bf16 v[82:97], v[50:53], v[146:149], v[82:97]
	v_add_f32_e32 v45, v22, v46
	v_sub_f32_e32 v6, v7, v217
	v_exp_f32_e32 v42, v6
	v_sub_f32_e32 v6, v23, v217
	v_exp_f32_e32 v44, v6
	s_waitcnt lgkmcnt(6)
	v_mfma_f32_32x32x16_bf16 v[82:97], v[54:57], v[130:133], v[82:97]
	v_cvt_pk_bf16_f32 v222, v46, v42
	v_add_f32_e64 v6, v44, v42
	v_add_f32_e64 v7, v45, v43
	v_add_f32_e32 v7, v6, v7
	v_cvt_pk_bf16_f32 v223, v22, v44
	v_sub_f32_e32 v6, v8, v217
	v_exp_f32_e32 v42, v6
	v_sub_f32_e32 v6, v24, v217
	v_exp_f32_e32 v24, v6
	s_waitcnt lgkmcnt(5)
	v_mfma_f32_32x32x16_bf16 v[82:97], v[58:61], v[154:157], v[82:97]
	v_add_f32_e32 v23, v24, v42
	v_sub_f32_e32 v6, v9, v217
	v_sub_f32_e32 v8, v25, v217
	v_exp_f32_e32 v6, v6
	v_exp_f32_e32 v22, v8
	s_waitcnt lgkmcnt(4)
; #define LAS __attribute__((address_space(3)))
; __device__ __forceinline__ unsigned pk2(float lo, float hi) { f32x2_t v = {lo, hi}; bf16x2_t b = __builtin_convertvector(v, bf16x2_t); return __builtin_bit_cast(unsigned, b); }
; #define MFMA32(a, b, c) __builtin_amdgcn_mfma_f32_32x32x16_bf16((a), (b), (c), 0, 0, 0)
; template <int DQK, int VAR> __device__ __forceinline__ void att_tile_fused(LAS unsigned char* lds, int kt, int mylast, bool& pend, int vs_prev, int vs_cur, int lane_off, int r, int h, ...
;     ...
; #pragma unroll
;     for (int db = 0; db < 4; ++db) {
;         if (db < 3) {
; #pragma unroll
;             for (int js = 0; js < 4; ++js) va[(db + 1) & 1][js] = *(const LAS bf16x8*)(vb + (db + 1) * 32 * VPB + js * 32);
;         }
; #pragma unroll
;         for (int js = 0; js < 4; ++js) {
;             const int c = db * 4 + js;
;             O[db] = MFMA32(va[db & 1][js], pf[js], O[db]);
;             S0[c] = __builtin_amdgcn_exp2f(S0[c] - mn); S1[c] = __builtin_amdgcn_exp2f(S1[c] - mn); ps += S0[c] + S1[c];
;             if (c & 1) {
;                 const unsigned a = pk2(S0[c - 1], S0[c]), b = pk2(S1[c - 1], S1[c]);
;                 const int q = c >> 1;
;                 if (q == 0) { w0.x = a; w2.x = b; } else if (q == 1) { w0.y = a; w2.y = b; } else if (q == 2) { w0.z = a; w2.z = b; } else if (q == 3) { w0.w = a; w2.w = b; }
;                 else if (q == 4) { w1.x = a; w3.x = b; } else if (q == 5) { w1.y = a; w3.y = b; } else if (q == 6) { w1.z = a; w3.z = b; } else { w1.w = a; w3.w = b; }
;             }
;             __builtin_amdgcn_sched_barrier(0);
;         }
;     }
;     lrun = lrun * alpha + ps;
;     alpha_p = alpha; grew_p = grew;
;     pf[0] = __builtin_bit_cast(bf16x8, w0); pf[1] = __builtin_bit_cast(bf16x8, w1); pf[2] = __builtin_bit_cast(bf16x8, w2); pf[3] = __builtin_bit_cast(bf16x8, w3);
;     pend = true;
	v_mfma_f32_32x32x16_bf16 v[82:97], v[62:65], v[134:137], v[82:97]
	v_cvt_pk_bf16_f32 v224, v42, v6
	v_add_f32_e64 v8, v22, v6
	v_add_f32_e64 v9, v23, v7
	v_cvt_pk_bf16_f32 v230, v24, v22
	v_add_f32_e64 v50, v8, v8
	v_add_f32_e64 v51, v8, v9
	ds_read_b128 v[6:9], v198 offset:65024
	ds_read_b128 v[22:25], v198 offset:65056
	ds_read_b128 v[42:45], v198 offset:65088
	ds_read_b128 v[46:49], v198 offset:65120
	v_sub_f32_e32 v10, v10, v217
	v_sub_f32_e32 v26, v26, v217
	v_exp_f32_e32 v10, v10
	v_exp_f32_e32 v26, v26
	s_waitcnt lgkmcnt(7)
	v_mfma_f32_32x32x16_bf16 v[98:113], v[2:5], v[146:149], v[98:113]
	v_add_f32_e32 v3, v26, v10
	v_sub_f32_e32 v2, v11, v217
	v_exp_f32_e32 v50, v2
	v_sub_f32_e32 v2, v27, v217
	v_exp_f32_e32 v2, v2
	s_waitcnt lgkmcnt(6)
	v_mfma_f32_32x32x16_bf16 v[98:113], v[18:21], v[130:133], v[98:113]
	v_cvt_pk_bf16_f32 v231, v10, v50
	v_add_f32_e64 v4, v2, v50
	v_add_f32_e64 v5, v3, v51
	v_add_f32_e32 v5, v4, v5
	v_cvt_pk_bf16_f32 v232, v26, v2
	v_sub_f32_e32 v2, v12, v217
	v_exp_f32_e32 v12, v2
	v_sub_f32_e32 v2, v28, v217
	v_exp_f32_e32 v18, v2
	s_waitcnt lgkmcnt(5)
	v_mfma_f32_32x32x16_bf16 v[98:113], v[34:37], v[154:157], v[98:113]
	v_add_f32_e32 v3, v18, v12
	v_sub_f32_e32 v2, v13, v217
	v_exp_f32_e32 v4, v2
	v_sub_f32_e32 v2, v29, v217
	v_exp_f32_e32 v2, v2
	s_waitcnt lgkmcnt(4)
	v_mfma_f32_32x32x16_bf16 v[98:113], v[38:41], v[134:137], v[98:113]
	v_cvt_pk_bf16_f32 v233, v12, v4
	v_add_f32_e64 v10, v2, v4
	v_add_f32_e64 v11, v3, v5
	v_add_f32_e32 v11, v10, v11
	v_cvt_pk_bf16_f32 v234, v18, v2
	v_sub_f32_e32 v2, v14, v217
	v_exp_f32_e32 v12, v2
	v_sub_f32_e32 v2, v30, v217
	v_exp_f32_e32 v13, v2
	s_waitcnt lgkmcnt(3)
	v_mfma_f32_32x32x16_bf16 v[114:129], v[6:9], v[146:149], v[114:129]
	v_add_f32_e32 v3, v13, v12
	v_sub_f32_e32 v2, v15, v217
	v_exp_f32_e32 v10, v2
	v_sub_f32_e32 v2, v31, v217
	v_exp_f32_e32 v2, v2
	s_waitcnt lgkmcnt(2)
	v_mfma_f32_32x32x16_bf16 v[114:129], v[22:25], v[130:133], v[114:129]
	v_cvt_pk_bf16_f32 v132, v12, v10
	v_add_f32_e64 v4, v2, v10
	v_add_f32_e64 v5, v3, v11
	v_add_f32_e32 v5, v4, v5
	v_cvt_pk_bf16_f32 v235, v13, v2
	v_sub_f32_e32 v2, v16, v217
	v_exp_f32_e32 v8, v2
	v_sub_f32_e32 v2, v32, v217
	v_exp_f32_e32 v9, v2
	s_waitcnt lgkmcnt(1)
	v_mfma_f32_32x32x16_bf16 v[114:129], v[42:45], v[154:157], v[114:129]
	v_add_f32_e32 v3, v9, v8
	v_sub_f32_e32 v2, v17, v217
	v_exp_f32_e32 v4, v2
	v_sub_f32_e32 v2, v33, v217
	v_exp_f32_e32 v2, v2
	s_waitcnt lgkmcnt(0)
	v_mfma_f32_32x32x16_bf16 v[114:129], v[46:49], v[134:137], v[114:129]
	v_cvt_pk_bf16_f32 v133, v8, v4
	v_add_f32_e64 v6, v2, v4
	v_add_f32_e64 v7, v3, v5
	v_add_f32_e32 v130, v6, v7
	v_cvt_pk_bf16_f32 v137, v9, v2
	v_exp_f32_e32 v198, v218
	s_nop 5
	v_mov_b64_e32 v[50:51], v[114:115]
	v_mov_b64_e32 v[34:35], v[98:99]
	v_mov_b64_e32 v[18:19], v[82:83]
	v_fmac_f32_e32 v130, v187, v198
	v_mov_b64_e32 v[2:3], v[66:67]
	v_mov_b64_e32 v[52:53], v[116:117]
	v_mov_b64_e32 v[54:55], v[118:119]
	v_mov_b64_e32 v[56:57], v[120:121]
	v_mov_b64_e32 v[58:59], v[122:123]
	v_mov_b64_e32 v[60:61], v[124:125]
	v_mov_b64_e32 v[62:63], v[126:127]
	v_mov_b64_e32 v[64:65], v[128:129]
	v_mov_b64_e32 v[36:37], v[100:101]
	v_mov_b64_e32 v[38:39], v[102:103]
	v_mov_b64_e32 v[40:41], v[104:105]
	v_mov_b64_e32 v[42:43], v[106:107]
	v_mov_b64_e32 v[44:45], v[108:109]
	v_mov_b64_e32 v[46:47], v[110:111]
	v_mov_b64_e32 v[48:49], v[112:113]
	v_mov_b64_e32 v[20:21], v[84:85]
	v_mov_b64_e32 v[22:23], v[86:87]
	v_mov_b64_e32 v[24:25], v[88:89]
	v_mov_b64_e32 v[26:27], v[90:91]
	v_mov_b64_e32 v[28:29], v[92:93]
	v_mov_b64_e32 v[30:31], v[94:95]
	v_mov_b64_e32 v[32:33], v[96:97]
	v_mov_b64_e32 v[4:5], v[68:69]
	v_mov_b64_e32 v[6:7], v[70:71]
	v_mov_b64_e32 v[8:9], v[72:73]
	v_mov_b64_e32 v[10:11], v[74:75]
	v_mov_b64_e32 v[12:13], v[76:77]
	v_mov_b64_e32 v[14:15], v[78:79]
	v_mov_b64_e32 v[16:17], v[80:81]
	v_mov_b32_e32 v216, v217
	v_mov_b32_e32 v187, v130
	v_mov_b32_e32 v146, v0
	v_mov_b32_e32 v147, v220
	v_mov_b32_e32 v148, v222
	v_mov_b32_e32 v149, v224
	v_mov_b32_e32 v130, v231
	v_mov_b32_e32 v131, v233
	v_mov_b32_e32 v154, v219
	v_mov_b32_e32 v155, v221
	v_mov_b32_e32 v156, v223
	v_mov_b32_e32 v157, v230
	v_mov_b32_e32 v134, v232
	v_mov_b32_e32 v135, v234
	v_mov_b32_e32 v136, v235
	s_andn2_b64 vcc, exec, s[26:27]
	s_cbranch_vccz .LBB0_853
	s_branch .LBB0_854
